# v18 + branch-A rescale block moved out of line (common path falls through into next tile's QK MFMAs)
# speedup vs baseline: 1.0015x; 1.0015x over previous
; template <int DK, bool NOMAX> ...
;     ...
;   for (int i = 0; i < 16; ++i) {
;     if (i + 2 < 16) VRD_((i + 2) % 3, i + 2);
;     if (i == 1) { if (dk) __builtin_amdgcn_global_load_lds((const unsigned*)gk0, lk, 16, 0, 0); }
;     if (i == 3) { if constexpr (DK == 128) { if (dk) __builtin_amdgcn_global_load_lds((const unsigned*)gk1, (lds_up)((lds_cp)lk + 8192), 16, 0, 0); } }
;     if (i == 5) { if (dv) __builtin_amdgcn_global_load_lds((const unsigned*)gv0, lv, 16, 0, 0); }
;     if (i == 7) { if (dv) __builtin_amdgcn_global_load_lds((const unsigned*)gv1, (lds_up)((lds_cp)lv + 8192), 16, 0, 0); }
;     if (i == 12 || i == 13) { const int cb_ = ((i - 12) * 16 + hi * 8) * 2;
;       if constexpr (DK == 128) { kf[i - 12][0] = *reinterpret_cast<const bf16x8*>(Kn + KSWZ128(r32, cb_)); kf[i - 12][1] = *reinterpret_cast<const bf16x8*>(Kn + KSWZ128(32 + r32, cb_)); }
;       else { kf[i - 12][0] = *reinterpret_cast<const bf16x8*>(Kn + KSWZ64(r32, cb_)); kf[i - 12][1] = *reinterpret_cast<const bf16x8*>(Kn + KSWZ64(32 + r32, cb_)); } }
;     SBAR();
;     o[i & 3] = __builtin_amdgcn_mfma_f32_32x32x16_bf16(pa[i >> 2], VFR_(i % 3), o[i & 3], 0, 0, 0);
;     if constexpr (NOMAX) { c0[i] = __builtin_amdgcn_exp2f(c0[i]); c1[i] = __builtin_amdgcn_exp2f(c1[i]); if (i > 0) { psa += c0[i - 1]; psb += c1[i - 1]; } PIN(c0); PIN(c1); PIN(psa); PIN(psb); }
;     else {
;     if (i == 0) { ma = max3f(c0[0], c0[1], c1[0]); mb = max3f(c0[2], c0[3], c1[1]); ma = max3f(ma, c1[2], c1[3]); }
;     if (i >= 1 && i <= 3) { const int r = 4 * i; ma = max3f(ma, c0[r], c0[r + 1]); mb = max3f(mb, c0[r + 2], c0[r + 3]); ma = max3f(ma, c1[r], c1[r + 1]); mb = max3f(mb, c1[r + 2], c1[r + 3]); }
;     if (i == 4) { float pmax = fmaxf(ma, mb);
;       { auto rr = __builtin_amdgcn_permlane32_swap(__float_as_uint(pmax), __float_as_uint(pmax), false, false);
;         pmax = fmaxf(__uint_as_float(rr[0]), __uint_as_float(rr[1])); }
;       pmax += cb;
;       const bool keep = __all(pmax - m_reg <= THR2);
;       const float mn = keep ? m_reg : fmaxf(m_reg, pmax);
;       alpha = __builtin_amdgcn_exp2f(m_reg - mn); m_reg = mn; mnC = cb - mn; }
;     if (i >= 5 && i <= 8) { const int r = 4 * (i - 5);
; #pragma unroll
;       for (int q = 0; q < 4; ++q) { c0[r + q] += mnC; c1[r + q] += mnC; } }
;     if (i >= 9) { const int r0 = (i - 9) * 2 + (i > 14 ? 1 : 0), n = i >= 14 ? 3 : 2;
; #pragma unroll
.LBB0_226:
	v_sub_f32_e32 v0, v212, v215
	v_exp_f32_e32 v0, v0
	s_add_i32 s4, s63, 0xffff8000
	s_and_b32 s4, s4, 0xc000
	s_add_i32 s94, s4, 0
	s_waitcnt lgkmcnt(4)
	v_mfma_f32_32x32x16_bf16 v[32:47], v[96:99], v[100:103], v[32:47]
	v_exp_f32_e32 v129, v129
	v_exp_f32_e32 v113, v113
	ds_read_b64_tr_b16 v[88:89], v213 offset:4096
	ds_read_b64_tr_b16 v[90:91], v213 offset:6144
	s_waitcnt lgkmcnt(4)
	v_mfma_f32_32x32x16_bf16 v[48:63], v[96:99], v[80:83], v[48:63]
	v_exp_f32_e32 v130, v130
	v_exp_f32_e32 v114, v114
	v_add_f32_e32 v100, v113, v112
	v_add_f32_e32 v101, v129, v128
	ds_read_b64_tr_b16 v[80:81], v213 offset:4608
	ds_read_b64_tr_b16 v[82:83], v213 offset:6656
	s_waitcnt lgkmcnt(4)
	v_mfma_f32_32x32x16_bf16 v[64:79], v[96:99], v[84:87], v[64:79]
	v_exp_f32_e32 v131, v131
	v_exp_f32_e32 v115, v115
	v_add_f32_e32 v96, v114, v100
	v_add_f32_e32 v97, v130, v101
	ds_read_b64_tr_b16 v[84:85], v213 offset:5120
	ds_read_b64_tr_b16 v[86:87], v213 offset:7168
	s_waitcnt lgkmcnt(4)
	v_mfma_f32_32x32x16_bf16 v[16:31], v[10:13], v[88:91], v[16:31]
	v_exp_f32_e32 v132, v132
	v_exp_f32_e32 v116, v116
	v_add_f32_e32 v96, v115, v96
	v_add_f32_e32 v97, v131, v97
	s_add_u32 vcc_lo, s0, s30
	s_addc_u32 vcc_hi, s1, s31
	s_add_i32 s4, s62, s58
	s_mov_b32 m0, s4
	ds_read_b64_tr_b16 v[88:89], v213 offset:5632
	ds_read_b64_tr_b16 v[90:91], v213 offset:7680
	global_load_lds_dwordx4 v160, vcc
	s_waitcnt lgkmcnt(4)
	v_mfma_f32_32x32x16_bf16 v[32:47], v[10:13], v[80:83], v[32:47]
	v_exp_f32_e32 v133, v133
	v_exp_f32_e32 v117, v117
	v_add_f32_e32 v92, v116, v96
	v_add_f32_e32 v93, v132, v97
	ds_read_b64_tr_b16 v[80:81], v213 offset:8192
	ds_read_b64_tr_b16 v[82:83], v213 offset:10240
	s_waitcnt lgkmcnt(4)
	v_mfma_f32_32x32x16_bf16 v[48:63], v[10:13], v[84:87], v[48:63]
	v_exp_f32_e32 v134, v134
	v_exp_f32_e32 v118, v118
	v_add_f32_e32 v92, v117, v92
	v_add_f32_e32 v93, v133, v93
	s_add_i32 m0, s4, 0x2000
	ds_read_b64_tr_b16 v[84:85], v213 offset:8704
	ds_read_b64_tr_b16 v[86:87], v213 offset:10752
	global_load_lds_dwordx4 v14, vcc
	s_waitcnt lgkmcnt(4)
	v_mfma_f32_32x32x16_bf16 v[64:79], v[10:13], v[88:91], v[64:79]
	v_exp_f32_e32 v135, v135
	v_exp_f32_e32 v119, v119
	v_add_f32_e32 v88, v118, v92
	v_add_f32_e32 v89, v134, v93
	ds_read_b64_tr_b16 v[10:11], v213 offset:9216
	ds_read_b64_tr_b16 v[12:13], v213 offset:11264
	s_waitcnt lgkmcnt(4)
	v_mfma_f32_32x32x16_bf16 v[16:31], v[6:9], v[80:83], v[16:31]
	v_exp_f32_e32 v136, v136
	v_exp_f32_e32 v120, v120
	v_add_f32_e32 v88, v119, v88
	v_add_f32_e32 v89, v135, v89
	ds_read_b64_tr_b16 v[80:81], v213 offset:9728
	ds_read_b64_tr_b16 v[82:83], v213 offset:11776
	s_waitcnt lgkmcnt(4)
	v_mfma_f32_32x32x16_bf16 v[32:47], v[6:9], v[84:87], v[32:47]
	v_exp_f32_e32 v137, v137
	v_exp_f32_e32 v121, v121
	v_add_f32_e32 v84, v120, v88
	v_add_f32_e32 v85, v136, v89
	ds_read_b64_tr_b16 v[88:89], v213 offset:12288
	ds_read_b64_tr_b16 v[90:91], v213 offset:14336
	s_waitcnt lgkmcnt(4)
	v_mfma_f32_32x32x16_bf16 v[48:63], v[6:9], v[10:13], v[48:63]
	v_exp_f32_e32 v138, v138
	v_exp_f32_e32 v122, v122
	v_add_f32_e32 v10, v121, v84
	v_add_f32_e32 v11, v137, v85
	ds_read_b64_tr_b16 v[92:93], v213 offset:12800
	ds_read_b64_tr_b16 v[94:95], v213 offset:14848
	s_waitcnt lgkmcnt(4)
	v_mfma_f32_32x32x16_bf16 v[64:79], v[6:9], v[80:83], v[64:79]
	v_exp_f32_e32 v139, v139
	v_exp_f32_e32 v123, v123
	v_add_f32_e32 v6, v122, v10
	v_add_f32_e32 v7, v138, v11
	v_add_u32_e32 v8, s94, v209
	ds_read_b64_tr_b16 v[96:97], v213 offset:13312
	ds_read_b64_tr_b16 v[98:99], v213 offset:15360
	ds_read_b128 v[80:83], v8
	ds_read_b128 v[84:87], v8 offset:4096
	s_waitcnt lgkmcnt(6)
	v_mfma_f32_32x32x16_bf16 v[16:31], v[2:5], v[88:91], v[16:31]
	v_exp_f32_e32 v140, v140
	v_exp_f32_e32 v124, v124
	v_add_f32_e32 v100, v123, v6
	v_add_f32_e32 v101, v139, v7
	v_add_u32_e32 v10, s94, v210
	ds_read_b64_tr_b16 v[88:89], v213 offset:13824
	ds_read_b64_tr_b16 v[90:91], v213 offset:15872
	ds_read_b128 v[6:9], v10
	ds_read_b128 v[10:13], v10 offset:4096
	s_waitcnt lgkmcnt(8)
	v_mfma_f32_32x32x16_bf16 v[32:47], v[2:5], v[92:95], v[32:47]
	v_exp_f32_e32 v141, v141
	v_exp_f32_e32 v125, v125
	v_add_f32_e32 v92, v124, v100
	v_add_f32_e32 v93, v140, v101
	s_waitcnt lgkmcnt(6)
	v_mfma_f32_32x32x16_bf16 v[48:63], v[2:5], v[96:99], v[48:63]
	v_exp_f32_e32 v142, v142
	v_exp_f32_e32 v126, v126
	v_add_f32_e32 v92, v125, v92
	v_add_f32_e32 v93, v141, v93
	s_waitcnt lgkmcnt(2)
	v_mfma_f32_32x32x16_bf16 v[64:79], v[2:5], v[88:91], v[64:79]
	v_exp_f32_e32 v143, v143
	v_exp_f32_e32 v127, v127
	v_add_f32_e32 v2, v126, v92
	v_add_f32_e32 v3, v142, v93
	s_nop 0
	v_add_f32_e32 v3, v143, v3
	v_add_f32_e32 v2, v127, v2
	v_add_f32_e32 v213, v3, v2
	v_mov_b32_e32 v214, v213
	s_nop 1
	v_permlane32_swap_b32_e32 v213, v214
	v_cmp_neq_f32_e32 vcc, 1.0, v0
	s_cbranch_vccnz .Lmy_resc_a1_1

; template <int DK, bool NOMAX> ...
;     ...
;   for (int i = 0; i < 16; ++i) {
;     if (i + 2 < 16) VRD_((i + 2) % 3, i + 2);
;     if (i == 1) { if (dk) __builtin_amdgcn_global_load_lds((const unsigned*)gk0, lk, 16, 0, 0); }
;     if (i == 3) { if constexpr (DK == 128) { if (dk) __builtin_amdgcn_global_load_lds((const unsigned*)gk1, (lds_up)((lds_cp)lk + 8192), 16, 0, 0); } }
;     if (i == 5) { if (dv) __builtin_amdgcn_global_load_lds((const unsigned*)gv0, lv, 16, 0, 0); }
;     if (i == 7) { if (dv) __builtin_amdgcn_global_load_lds((const unsigned*)gv1, (lds_up)((lds_cp)lv + 8192), 16, 0, 0); }
;     if (i == 12 || i == 13) { const int cb_ = ((i - 12) * 16 + hi * 8) * 2;
;       if constexpr (DK == 128) { kf[i - 12][0] = *reinterpret_cast<const bf16x8*>(Kn + KSWZ128(r32, cb_)); kf[i - 12][1] = *reinterpret_cast<const bf16x8*>(Kn + KSWZ128(32 + r32, cb_)); }
;       else { kf[i - 12][0] = *reinterpret_cast<const bf16x8*>(Kn + KSWZ64(r32, cb_)); kf[i - 12][1] = *reinterpret_cast<const bf16x8*>(Kn + KSWZ64(32 + r32, cb_)); } }
;     SBAR();
;     o[i & 3] = __builtin_amdgcn_mfma_f32_32x32x16_bf16(pa[i >> 2], VFR_(i % 3), o[i & 3], 0, 0, 0);
;     if constexpr (NOMAX) { c0[i] = __builtin_amdgcn_exp2f(c0[i]); c1[i] = __builtin_amdgcn_exp2f(c1[i]); if (i > 0) { psa += c0[i - 1]; psb += c1[i - 1]; } PIN(c0); PIN(c1); PIN(psa); PIN(psb); }
;     else {
;     if (i == 0) { ma = max3f(c0[0], c0[1], c1[0]); mb = max3f(c0[2], c0[3], c1[1]); ma = max3f(ma, c1[2], c1[3]); }
;     if (i >= 1 && i <= 3) { const int r = 4 * i; ma = max3f(ma, c0[r], c0[r + 1]); mb = max3f(mb, c0[r + 2], c0[r + 3]); ma = max3f(ma, c1[r], c1[r + 1]); mb = max3f(mb, c1[r + 2], c1[r + 3]); }
;     if (i == 4) { float pmax = fmaxf(ma, mb);
;       { auto rr = __builtin_amdgcn_permlane32_swap(__float_as_uint(pmax), __float_as_uint(pmax), false, false);
;         pmax = fmaxf(__uint_as_float(rr[0]), __uint_as_float(rr[1])); }
;       pmax += cb;
;       const bool keep = __all(pmax - m_reg <= THR2);
;       const float mn = keep ? m_reg : fmaxf(m_reg, pmax);
;       alpha = __builtin_amdgcn_exp2f(m_reg - mn); m_reg = mn; mnC = cb - mn; }
;     if (i >= 5 && i <= 8) { const int r = 4 * (i - 5);
; #pragma unroll
;       for (int q = 0; q < 4; ++q) { c0[r + q] += mnC; c1[r + q] += mnC; } }
;     if (i >= 9) { const int r0 = (i - 9) * 2 + (i > 14 ? 1 : 0), n = i >= 14 ? 3 : 2;
; #pragma unroll
.LBB0_240:
	v_sub_f32_e32 v120, v215, v212
	v_exp_f32_e32 v120, v120
	s_add_i32 s59, s63, 0xffffc000
	s_and_b32 s59, s59, 0xc000
	s_add_i32 s59, s59, 0
	s_waitcnt lgkmcnt(4)
	v_mfma_f32_32x32x16_bf16 v[32:47], v[128:131], v[132:135], v[32:47]
	v_exp_f32_e32 v97, v97
	v_exp_f32_e32 v81, v81
	ds_read_b64_tr_b16 v[122:123], v217 offset:4096
	ds_read_b64_tr_b16 v[124:125], v217 offset:6144
	s_waitcnt lgkmcnt(4)
	v_mfma_f32_32x32x16_bf16 v[48:63], v[128:131], v[112:115], v[48:63]
	v_exp_f32_e32 v98, v98
	v_exp_f32_e32 v82, v82
	v_add_f32_e32 v132, v81, v80
	v_add_f32_e32 v121, v97, v96
	ds_read_b64_tr_b16 v[112:113], v217 offset:4608
	ds_read_b64_tr_b16 v[114:115], v217 offset:6656
	s_waitcnt lgkmcnt(4)
	v_mfma_f32_32x32x16_bf16 v[64:79], v[128:131], v[116:119], v[64:79]
	v_exp_f32_e32 v99, v99
	v_exp_f32_e32 v83, v83
	v_add_f32_e32 v128, v82, v132
	v_add_f32_e32 v121, v98, v121
	ds_read_b64_tr_b16 v[116:117], v217 offset:5120
	ds_read_b64_tr_b16 v[118:119], v217 offset:7168
	s_waitcnt lgkmcnt(4)
	v_mfma_f32_32x32x16_bf16 v[16:31], v[10:13], v[122:125], v[16:31]
	v_exp_f32_e32 v100, v100
	v_exp_f32_e32 v84, v84
	v_add_f32_e32 v128, v83, v128
	v_add_f32_e32 v121, v99, v121
	s_add_u32 vcc_lo, s0, s36
	s_addc_u32 vcc_hi, s1, s37
	s_add_i32 s94, s62, s96
	s_mov_b32 m0, s94
	ds_read_b64_tr_b16 v[122:123], v217 offset:5632
	ds_read_b64_tr_b16 v[124:125], v217 offset:7680
	global_load_lds_dwordx4 v160, vcc
	s_waitcnt lgkmcnt(4)
	v_mfma_f32_32x32x16_bf16 v[32:47], v[10:13], v[112:115], v[32:47]
	v_exp_f32_e32 v101, v101
	v_exp_f32_e32 v85, v85
	v_add_f32_e32 v126, v84, v128
	v_add_f32_e32 v121, v100, v121
	ds_read_b64_tr_b16 v[112:113], v217 offset:8192
	ds_read_b64_tr_b16 v[114:115], v217 offset:10240
	s_waitcnt lgkmcnt(4)
	v_mfma_f32_32x32x16_bf16 v[48:63], v[10:13], v[116:119], v[48:63]
	v_exp_f32_e32 v102, v102
	v_exp_f32_e32 v86, v86
	v_add_f32_e32 v126, v85, v126
	v_add_f32_e32 v121, v101, v121
	s_add_i32 m0, s94, 0x2000
	ds_read_b64_tr_b16 v[116:117], v217 offset:8704
	ds_read_b64_tr_b16 v[118:119], v217 offset:10752
	global_load_lds_dwordx4 v14, vcc
	s_waitcnt lgkmcnt(4)
	v_mfma_f32_32x32x16_bf16 v[64:79], v[10:13], v[122:125], v[64:79]
	v_exp_f32_e32 v103, v103
	v_exp_f32_e32 v87, v87
	v_add_f32_e32 v122, v86, v126
	v_add_f32_e32 v121, v102, v121
	ds_read_b64_tr_b16 v[10:11], v217 offset:9216
	ds_read_b64_tr_b16 v[12:13], v217 offset:11264
	s_waitcnt lgkmcnt(4)
	v_mfma_f32_32x32x16_bf16 v[16:31], v[6:9], v[112:115], v[16:31]
	v_exp_f32_e32 v104, v104
	v_exp_f32_e32 v88, v88
	v_add_f32_e32 v122, v87, v122
	v_add_f32_e32 v121, v103, v121
	ds_read_b64_tr_b16 v[112:113], v217 offset:9728
	ds_read_b64_tr_b16 v[114:115], v217 offset:11776
	s_waitcnt lgkmcnt(4)
	v_mfma_f32_32x32x16_bf16 v[32:47], v[6:9], v[116:119], v[32:47]
	v_exp_f32_e32 v105, v105
	v_exp_f32_e32 v89, v89
	v_add_f32_e32 v116, v88, v122
	v_add_f32_e32 v117, v104, v121
	ds_read_b64_tr_b16 v[122:123], v217 offset:12288
	ds_read_b64_tr_b16 v[124:125], v217 offset:14336
	s_waitcnt lgkmcnt(4)
	v_mfma_f32_32x32x16_bf16 v[48:63], v[6:9], v[10:13], v[48:63]
	v_exp_f32_e32 v106, v106
	v_exp_f32_e32 v90, v90
	v_add_f32_e32 v10, v89, v116
	v_add_f32_e32 v11, v105, v117
	ds_read_b64_tr_b16 v[126:127], v217 offset:12800
	ds_read_b64_tr_b16 v[128:129], v217 offset:14848
	s_waitcnt lgkmcnt(4)
	v_mfma_f32_32x32x16_bf16 v[64:79], v[6:9], v[112:115], v[64:79]
	v_exp_f32_e32 v107, v107
	v_exp_f32_e32 v91, v91
	v_add_f32_e32 v6, v90, v10
	v_add_f32_e32 v7, v106, v11
	v_add_u32_e32 v8, s59, v209
	ds_read_b64_tr_b16 v[130:131], v217 offset:13312
	ds_read_b64_tr_b16 v[132:133], v217 offset:15360
	ds_read_b128 v[116:119], v8
	ds_read_b128 v[112:115], v8 offset:4096
	s_waitcnt lgkmcnt(6)
	v_mfma_f32_32x32x16_bf16 v[16:31], v[2:5], v[122:125], v[16:31]
	v_exp_f32_e32 v108, v108
	v_exp_f32_e32 v92, v92
	v_add_f32_e32 v121, v91, v6
	v_add_f32_e32 v134, v107, v7
	v_add_u32_e32 v6, s59, v210
	ds_read_b64_tr_b16 v[122:123], v217 offset:13824
	ds_read_b64_tr_b16 v[124:125], v217 offset:15872
	ds_read_b128 v[10:13], v6
	ds_read_b128 v[6:9], v6 offset:4096
	s_waitcnt lgkmcnt(8)
	v_mfma_f32_32x32x16_bf16 v[32:47], v[2:5], v[126:129], v[32:47]
	v_exp_f32_e32 v109, v109
	v_exp_f32_e32 v93, v93
	v_add_f32_e32 v121, v92, v121
	v_add_f32_e32 v126, v108, v134
	s_waitcnt lgkmcnt(6)
	v_mfma_f32_32x32x16_bf16 v[48:63], v[2:5], v[130:133], v[48:63]
	v_exp_f32_e32 v110, v110
	v_exp_f32_e32 v94, v94
	v_add_f32_e32 v121, v93, v121
	v_add_f32_e32 v126, v109, v126
	s_waitcnt lgkmcnt(2)
	v_mfma_f32_32x32x16_bf16 v[64:79], v[2:5], v[122:125], v[64:79]
	v_exp_f32_e32 v111, v111
	v_exp_f32_e32 v95, v95
	v_add_f32_e32 v2, v94, v121
	v_add_f32_e32 v3, v110, v126
	s_nop 0
	v_add_f32_e32 v3, v111, v3
	v_add_f32_e32 v2, v95, v2
	v_add_f32_e32 v2, v3, v2
	v_mov_b32_e32 v3, v2
	s_nop 1
	v_permlane32_swap_b32_e32 v2, v3
	v_cmp_neq_f32_e32 vcc, 1.0, v120
	s_cbranch_vccnz .Lmy_resc_a1_2

.Lmy_resc_a1_1:
	s_and_saveexec_b64 s[4:5], s[46:47]
	ds_write_b32 v188, v0 offset:128
	s_or_b64 exec, exec, s[4:5]
	s_waitcnt lgkmcnt(0)
	v_add_u32_e32 v96, s2, v171
	ds_read_b128 v[2:5], v96 offset:224
	ds_read_b128 v[88:91], v96 offset:192
	ds_read_b128 v[92:95], v96 offset:160
	ds_read_b128 v[96:99], v96 offset:128
	s_waitcnt lgkmcnt(0)
	v_pk_mul_f32 v[28:29], v[28:29], v[2:3]
	v_pk_mul_f32 v[24:25], v[24:25], v[88:89]
	v_pk_mul_f32 v[20:21], v[20:21], v[92:93]
	v_pk_mul_f32 v[30:31], v[30:31], v[4:5]
	v_pk_mul_f32 v[26:27], v[26:27], v[90:91]
	v_pk_mul_f32 v[22:23], v[22:23], v[94:95]
	v_pk_mul_f32 v[18:19], v[18:19], v[98:99]
	v_pk_mul_f32 v[16:17], v[16:17], v[96:97]
	v_pk_mul_f32 v[44:45], v[44:45], v[2:3]
	v_pk_mul_f32 v[40:41], v[40:41], v[88:89]
	v_pk_mul_f32 v[36:37], v[36:37], v[92:93]
	v_pk_mul_f32 v[46:47], v[46:47], v[4:5]
	v_pk_mul_f32 v[42:43], v[42:43], v[90:91]
	v_pk_mul_f32 v[38:39], v[38:39], v[94:95]
	v_pk_mul_f32 v[34:35], v[34:35], v[98:99]
	v_pk_mul_f32 v[32:33], v[32:33], v[96:97]
	v_pk_mul_f32 v[60:61], v[60:61], v[2:3]
	v_pk_mul_f32 v[56:57], v[56:57], v[88:89]
	v_pk_mul_f32 v[52:53], v[52:53], v[92:93]
	v_pk_mul_f32 v[62:63], v[62:63], v[4:5]
	v_pk_mul_f32 v[58:59], v[58:59], v[90:91]
	v_pk_mul_f32 v[54:55], v[54:55], v[94:95]
	v_pk_mul_f32 v[50:51], v[50:51], v[98:99]
	v_pk_mul_f32 v[48:49], v[48:49], v[96:97]
	v_pk_mul_f32 v[76:77], v[76:77], v[2:3]
	v_pk_mul_f32 v[72:73], v[72:73], v[88:89]
	v_pk_mul_f32 v[68:69], v[68:69], v[92:93]
	v_pk_mul_f32 v[78:79], v[78:79], v[4:5]
	v_pk_mul_f32 v[74:75], v[74:75], v[90:91]
	v_pk_mul_f32 v[70:71], v[70:71], v[94:95]
	v_pk_mul_f32 v[66:67], v[66:67], v[98:99]
	v_pk_mul_f32 v[64:65], v[64:65], v[96:97]
	s_branch .LBB0_230
.Lmy_resc_a1_2:
	s_and_saveexec_b64 s[94:95], s[46:47]
	ds_write_b32 v188, v120 offset:128
	s_or_b64 exec, exec, s[94:95]
	s_waitcnt lgkmcnt(0)
	v_add_u32_e32 v4, s2, v171
	ds_read_b128 v[122:125], v4 offset:224
	ds_read_b128 v[126:129], v4 offset:192
	ds_read_b128 v[130:133], v4 offset:160
	ds_read_b128 v[134:137], v4 offset:128
	s_waitcnt lgkmcnt(0)
	v_pk_mul_f32 v[28:29], v[28:29], v[122:123]
	v_pk_mul_f32 v[24:25], v[24:25], v[126:127]
	v_pk_mul_f32 v[20:21], v[20:21], v[130:131]
	v_pk_mul_f32 v[30:31], v[30:31], v[124:125]
	v_pk_mul_f32 v[26:27], v[26:27], v[128:129]
	v_pk_mul_f32 v[22:23], v[22:23], v[132:133]
	v_pk_mul_f32 v[18:19], v[18:19], v[136:137]
	v_pk_mul_f32 v[16:17], v[16:17], v[134:135]
	v_pk_mul_f32 v[44:45], v[44:45], v[122:123]
	v_pk_mul_f32 v[40:41], v[40:41], v[126:127]
	v_pk_mul_f32 v[36:37], v[36:37], v[130:131]
	v_pk_mul_f32 v[46:47], v[46:47], v[124:125]
	v_pk_mul_f32 v[42:43], v[42:43], v[128:129]
	v_pk_mul_f32 v[38:39], v[38:39], v[132:133]
	v_pk_mul_f32 v[34:35], v[34:35], v[136:137]
	v_pk_mul_f32 v[32:33], v[32:33], v[134:135]
	v_pk_mul_f32 v[60:61], v[60:61], v[122:123]
	v_pk_mul_f32 v[56:57], v[56:57], v[126:127]
	v_pk_mul_f32 v[52:53], v[52:53], v[130:131]
	v_pk_mul_f32 v[62:63], v[62:63], v[124:125]
	v_pk_mul_f32 v[58:59], v[58:59], v[128:129]
	v_pk_mul_f32 v[54:55], v[54:55], v[132:133]
	v_pk_mul_f32 v[50:51], v[50:51], v[136:137]
	v_pk_mul_f32 v[48:49], v[48:49], v[134:135]
	v_pk_mul_f32 v[76:77], v[76:77], v[122:123]
	v_pk_mul_f32 v[72:73], v[72:73], v[126:127]
	v_pk_mul_f32 v[68:69], v[68:69], v[130:131]
	v_pk_mul_f32 v[78:79], v[78:79], v[124:125]
	v_pk_mul_f32 v[74:75], v[74:75], v[128:129]
	v_pk_mul_f32 v[70:71], v[70:71], v[132:133]
	v_pk_mul_f32 v[66:67], v[66:67], v[136:137]
	v_pk_mul_f32 v[64:65], v[64:65], v[134:135]
	s_branch .LBB0_244

; template <int DK, bool NOMAX> ...
;     ...
;   for (int i = 0; i < 16; ++i) {
;     if (i + 2 < 16) VRD_((i + 2) % 3, i + 2);
;     if (i == 1) { if (dk) __builtin_amdgcn_global_load_lds((const unsigned*)gk0, lk, 16, 0, 0); }
;     if (i == 3) { if constexpr (DK == 128) { if (dk) __builtin_amdgcn_global_load_lds((const unsigned*)gk1, (lds_up)((lds_cp)lk + 8192), 16, 0, 0); } }
;     if (i == 5) { if (dv) __builtin_amdgcn_global_load_lds((const unsigned*)gv0, lv, 16, 0, 0); }
;     if (i == 7) { if (dv) __builtin_amdgcn_global_load_lds((const unsigned*)gv1, (lds_up)((lds_cp)lv + 8192), 16, 0, 0); }
;     if (i == 12 || i == 13) { const int cb_ = ((i - 12) * 16 + hi * 8) * 2;
;       if constexpr (DK == 128) { kf[i - 12][0] = *reinterpret_cast<const bf16x8*>(Kn + KSWZ128(r32, cb_)); kf[i - 12][1] = *reinterpret_cast<const bf16x8*>(Kn + KSWZ128(32 + r32, cb_)); }
;       else { kf[i - 12][0] = *reinterpret_cast<const bf16x8*>(Kn + KSWZ64(r32, cb_)); kf[i - 12][1] = *reinterpret_cast<const bf16x8*>(Kn + KSWZ64(32 + r32, cb_)); } }
;     SBAR();
;     o[i & 3] = __builtin_amdgcn_mfma_f32_32x32x16_bf16(pa[i >> 2], VFR_(i % 3), o[i & 3], 0, 0, 0);
;     if constexpr (NOMAX) { c0[i] = __builtin_amdgcn_exp2f(c0[i]); c1[i] = __builtin_amdgcn_exp2f(c1[i]); if (i > 0) { psa += c0[i - 1]; psb += c1[i - 1]; } PIN(c0); PIN(c1); PIN(psa); PIN(psb); }
;     else {
;     if (i == 0) { ma = max3f(c0[0], c0[1], c1[0]); mb = max3f(c0[2], c0[3], c1[1]); ma = max3f(ma, c1[2], c1[3]); }
;     if (i >= 1 && i <= 3) { const int r = 4 * i; ma = max3f(ma, c0[r], c0[r + 1]); mb = max3f(mb, c0[r + 2], c0[r + 3]); ma = max3f(ma, c1[r], c1[r + 1]); mb = max3f(mb, c1[r + 2], c1[r + 3]); }
;     if (i == 4) { float pmax = fmaxf(ma, mb);
;       { auto rr = __builtin_amdgcn_permlane32_swap(__float_as_uint(pmax), __float_as_uint(pmax), false, false);
;         pmax = fmaxf(__uint_as_float(rr[0]), __uint_as_float(rr[1])); }
;       pmax += cb;
;       const bool keep = __all(pmax - m_reg <= THR2);
;       const float mn = keep ? m_reg : fmaxf(m_reg, pmax);
;       alpha = __builtin_amdgcn_exp2f(m_reg - mn); m_reg = mn; mnC = cb - mn; }
;     if (i >= 5 && i <= 8) { const int r = 4 * (i - 5);
; #pragma unroll
;       for (int q = 0; q < 4; ++q) { c0[r + q] += mnC; c1[r + q] += mnC; } }
;     if (i >= 9) { const int r0 = (i - 9) * 2 + (i > 14 ? 1 : 0), n = i >= 14 ? 3 : 2;
; #pragma unroll
.LBB0_319:
	v_sub_f32_e32 v0, v212, v215
	v_exp_f32_e32 v0, v0
	s_add_i32 s4, s63, 0xffff8000
	s_and_b32 s4, s4, 0xc000
	s_add_i32 s18, s4, 0
	s_waitcnt lgkmcnt(4)
	v_mfma_f32_32x32x16_bf16 v[32:47], v[96:99], v[100:103], v[32:47]
	v_exp_f32_e32 v129, v129
	v_exp_f32_e32 v113, v113
	ds_read_b64_tr_b16 v[88:89], v213 offset:4096
	ds_read_b64_tr_b16 v[90:91], v213 offset:6144
	s_waitcnt lgkmcnt(4)
	v_mfma_f32_32x32x16_bf16 v[48:63], v[96:99], v[80:83], v[48:63]
	v_exp_f32_e32 v130, v130
	v_exp_f32_e32 v114, v114
	v_add_f32_e32 v100, v113, v112
	v_add_f32_e32 v101, v129, v128
	ds_read_b64_tr_b16 v[80:81], v213 offset:4608
	ds_read_b64_tr_b16 v[82:83], v213 offset:6656
	s_waitcnt lgkmcnt(4)
	v_mfma_f32_32x32x16_bf16 v[64:79], v[96:99], v[84:87], v[64:79]
	v_exp_f32_e32 v131, v131
	v_exp_f32_e32 v115, v115
	v_add_f32_e32 v96, v114, v100
	v_add_f32_e32 v97, v130, v101
	ds_read_b64_tr_b16 v[84:85], v213 offset:5120
	ds_read_b64_tr_b16 v[86:87], v213 offset:7168
	s_waitcnt lgkmcnt(4)
	v_mfma_f32_32x32x16_bf16 v[16:31], v[10:13], v[88:91], v[16:31]
	v_exp_f32_e32 v132, v132
	v_exp_f32_e32 v116, v116
	v_add_f32_e32 v96, v115, v96
	v_add_f32_e32 v97, v131, v97
	s_add_u32 vcc_lo, s0, s30
	s_addc_u32 vcc_hi, s1, s31
	s_add_i32 s4, s62, s97
	s_mov_b32 m0, s4
	ds_read_b64_tr_b16 v[88:89], v213 offset:5632
	ds_read_b64_tr_b16 v[90:91], v213 offset:7680
	global_load_lds_dwordx4 v160, vcc
	s_waitcnt lgkmcnt(4)
	v_mfma_f32_32x32x16_bf16 v[32:47], v[10:13], v[80:83], v[32:47]
	v_exp_f32_e32 v133, v133
	v_exp_f32_e32 v117, v117
	v_add_f32_e32 v92, v116, v96
	v_add_f32_e32 v93, v132, v97
	ds_read_b64_tr_b16 v[80:81], v213 offset:8192
	ds_read_b64_tr_b16 v[82:83], v213 offset:10240
	s_waitcnt lgkmcnt(4)
	v_mfma_f32_32x32x16_bf16 v[48:63], v[10:13], v[84:87], v[48:63]
	v_exp_f32_e32 v134, v134
	v_exp_f32_e32 v118, v118
	v_add_f32_e32 v92, v117, v92
	v_add_f32_e32 v93, v133, v93
	s_add_i32 m0, s4, 0x2000
	ds_read_b64_tr_b16 v[84:85], v213 offset:8704
	ds_read_b64_tr_b16 v[86:87], v213 offset:10752
	global_load_lds_dwordx4 v14, vcc
	s_waitcnt lgkmcnt(4)
	v_mfma_f32_32x32x16_bf16 v[64:79], v[10:13], v[88:91], v[64:79]
	v_exp_f32_e32 v135, v135
	v_exp_f32_e32 v119, v119
	v_add_f32_e32 v88, v118, v92
	v_add_f32_e32 v89, v134, v93
	ds_read_b64_tr_b16 v[10:11], v213 offset:9216
	ds_read_b64_tr_b16 v[12:13], v213 offset:11264
	s_waitcnt lgkmcnt(4)
	v_mfma_f32_32x32x16_bf16 v[16:31], v[6:9], v[80:83], v[16:31]
	v_exp_f32_e32 v136, v136
	v_exp_f32_e32 v120, v120
	v_add_f32_e32 v88, v119, v88
	v_add_f32_e32 v89, v135, v89
	ds_read_b64_tr_b16 v[80:81], v213 offset:9728
	ds_read_b64_tr_b16 v[82:83], v213 offset:11776
	s_waitcnt lgkmcnt(4)
	v_mfma_f32_32x32x16_bf16 v[32:47], v[6:9], v[84:87], v[32:47]
	v_exp_f32_e32 v137, v137
	v_exp_f32_e32 v121, v121
	v_add_f32_e32 v84, v120, v88
	v_add_f32_e32 v85, v136, v89
	ds_read_b64_tr_b16 v[88:89], v213 offset:12288
	ds_read_b64_tr_b16 v[90:91], v213 offset:14336
	s_waitcnt lgkmcnt(4)
	v_mfma_f32_32x32x16_bf16 v[48:63], v[6:9], v[10:13], v[48:63]
	v_exp_f32_e32 v138, v138
	v_exp_f32_e32 v122, v122
	v_add_f32_e32 v10, v121, v84
	v_add_f32_e32 v11, v137, v85
	ds_read_b64_tr_b16 v[92:93], v213 offset:12800
	ds_read_b64_tr_b16 v[94:95], v213 offset:14848
	s_waitcnt lgkmcnt(4)
	v_mfma_f32_32x32x16_bf16 v[64:79], v[6:9], v[80:83], v[64:79]
	v_exp_f32_e32 v139, v139
	v_exp_f32_e32 v123, v123
	v_add_f32_e32 v6, v122, v10
	v_add_f32_e32 v7, v138, v11
	v_add_u32_e32 v8, s18, v209
	ds_read_b64_tr_b16 v[96:97], v213 offset:13312
	ds_read_b64_tr_b16 v[98:99], v213 offset:15360
	ds_read_b128 v[80:83], v8
	ds_read_b128 v[84:87], v8 offset:4096
	s_waitcnt lgkmcnt(6)
	v_mfma_f32_32x32x16_bf16 v[16:31], v[2:5], v[88:91], v[16:31]
	v_exp_f32_e32 v140, v140
	v_exp_f32_e32 v124, v124
	v_add_f32_e32 v100, v123, v6
	v_add_f32_e32 v101, v139, v7
	v_add_u32_e32 v10, s18, v210
	ds_read_b64_tr_b16 v[88:89], v213 offset:13824
	ds_read_b64_tr_b16 v[90:91], v213 offset:15872
	ds_read_b128 v[6:9], v10
	ds_read_b128 v[10:13], v10 offset:4096
	s_waitcnt lgkmcnt(8)
	v_mfma_f32_32x32x16_bf16 v[32:47], v[2:5], v[92:95], v[32:47]
	v_exp_f32_e32 v141, v141
	v_exp_f32_e32 v125, v125
	v_add_f32_e32 v92, v124, v100
	v_add_f32_e32 v93, v140, v101
	s_waitcnt lgkmcnt(6)
	v_mfma_f32_32x32x16_bf16 v[48:63], v[2:5], v[96:99], v[48:63]
	v_exp_f32_e32 v142, v142
	v_exp_f32_e32 v126, v126
	v_add_f32_e32 v92, v125, v92
	v_add_f32_e32 v93, v141, v93
	s_waitcnt lgkmcnt(2)
	v_mfma_f32_32x32x16_bf16 v[64:79], v[2:5], v[88:91], v[64:79]
	v_exp_f32_e32 v143, v143
	v_exp_f32_e32 v127, v127
	v_add_f32_e32 v2, v126, v92
	v_add_f32_e32 v3, v142, v93
	s_nop 0
	v_add_f32_e32 v3, v143, v3
	v_add_f32_e32 v2, v127, v2
	v_add_f32_e32 v213, v3, v2
	v_mov_b32_e32 v214, v213
	s_nop 1
	v_permlane32_swap_b32_e32 v213, v214
	v_cmp_neq_f32_e32 vcc, 1.0, v0
	s_cbranch_vccnz .Lmy_resc_a2_1

; template <int DK, bool NOMAX> ...
;     ...
;   for (int i = 0; i < 16; ++i) {
;     if (i + 2 < 16) VRD_((i + 2) % 3, i + 2);
;     if (i == 1) { if (dk) __builtin_amdgcn_global_load_lds((const unsigned*)gk0, lk, 16, 0, 0); }
;     if (i == 3) { if constexpr (DK == 128) { if (dk) __builtin_amdgcn_global_load_lds((const unsigned*)gk1, (lds_up)((lds_cp)lk + 8192), 16, 0, 0); } }
;     if (i == 5) { if (dv) __builtin_amdgcn_global_load_lds((const unsigned*)gv0, lv, 16, 0, 0); }
;     if (i == 7) { if (dv) __builtin_amdgcn_global_load_lds((const unsigned*)gv1, (lds_up)((lds_cp)lv + 8192), 16, 0, 0); }
;     if (i == 12 || i == 13) { const int cb_ = ((i - 12) * 16 + hi * 8) * 2;
;       if constexpr (DK == 128) { kf[i - 12][0] = *reinterpret_cast<const bf16x8*>(Kn + KSWZ128(r32, cb_)); kf[i - 12][1] = *reinterpret_cast<const bf16x8*>(Kn + KSWZ128(32 + r32, cb_)); }
;       else { kf[i - 12][0] = *reinterpret_cast<const bf16x8*>(Kn + KSWZ64(r32, cb_)); kf[i - 12][1] = *reinterpret_cast<const bf16x8*>(Kn + KSWZ64(32 + r32, cb_)); } }
;     SBAR();
;     o[i & 3] = __builtin_amdgcn_mfma_f32_32x32x16_bf16(pa[i >> 2], VFR_(i % 3), o[i & 3], 0, 0, 0);
;     if constexpr (NOMAX) { c0[i] = __builtin_amdgcn_exp2f(c0[i]); c1[i] = __builtin_amdgcn_exp2f(c1[i]); if (i > 0) { psa += c0[i - 1]; psb += c1[i - 1]; } PIN(c0); PIN(c1); PIN(psa); PIN(psb); }
;     else {
;     if (i == 0) { ma = max3f(c0[0], c0[1], c1[0]); mb = max3f(c0[2], c0[3], c1[1]); ma = max3f(ma, c1[2], c1[3]); }
;     if (i >= 1 && i <= 3) { const int r = 4 * i; ma = max3f(ma, c0[r], c0[r + 1]); mb = max3f(mb, c0[r + 2], c0[r + 3]); ma = max3f(ma, c1[r], c1[r + 1]); mb = max3f(mb, c1[r + 2], c1[r + 3]); }
;     if (i == 4) { float pmax = fmaxf(ma, mb);
;       { auto rr = __builtin_amdgcn_permlane32_swap(__float_as_uint(pmax), __float_as_uint(pmax), false, false);
;         pmax = fmaxf(__uint_as_float(rr[0]), __uint_as_float(rr[1])); }
;       pmax += cb;
;       const bool keep = __all(pmax - m_reg <= THR2);
;       const float mn = keep ? m_reg : fmaxf(m_reg, pmax);
;       alpha = __builtin_amdgcn_exp2f(m_reg - mn); m_reg = mn; mnC = cb - mn; }
;     if (i >= 5 && i <= 8) { const int r = 4 * (i - 5);
; #pragma unroll
;       for (int q = 0; q < 4; ++q) { c0[r + q] += mnC; c1[r + q] += mnC; } }
;     if (i >= 9) { const int r0 = (i - 9) * 2 + (i > 14 ? 1 : 0), n = i >= 14 ? 3 : 2;
; #pragma unroll
.LBB0_333:
	v_sub_f32_e32 v120, v215, v212
	v_exp_f32_e32 v120, v120
	s_add_i32 s18, s63, 0xffffc000
	s_and_b32 s18, s18, 0xc000
	s_add_i32 s18, s18, 0
	s_waitcnt lgkmcnt(4)
	v_mfma_f32_32x32x16_bf16 v[32:47], v[128:131], v[132:135], v[32:47]
	v_exp_f32_e32 v97, v97
	v_exp_f32_e32 v81, v81
	ds_read_b64_tr_b16 v[122:123], v217 offset:4096
	ds_read_b64_tr_b16 v[124:125], v217 offset:6144
	s_waitcnt lgkmcnt(4)
	v_mfma_f32_32x32x16_bf16 v[48:63], v[128:131], v[112:115], v[48:63]
	v_exp_f32_e32 v98, v98
	v_exp_f32_e32 v82, v82
	v_add_f32_e32 v132, v81, v80
	v_add_f32_e32 v121, v97, v96
	ds_read_b64_tr_b16 v[112:113], v217 offset:4608
	ds_read_b64_tr_b16 v[114:115], v217 offset:6656
	s_waitcnt lgkmcnt(4)
	v_mfma_f32_32x32x16_bf16 v[64:79], v[128:131], v[116:119], v[64:79]
	v_exp_f32_e32 v99, v99
	v_exp_f32_e32 v83, v83
	v_add_f32_e32 v128, v82, v132
	v_add_f32_e32 v121, v98, v121
	ds_read_b64_tr_b16 v[116:117], v217 offset:5120
	ds_read_b64_tr_b16 v[118:119], v217 offset:7168
	s_waitcnt lgkmcnt(4)
	v_mfma_f32_32x32x16_bf16 v[16:31], v[10:13], v[122:125], v[16:31]
	v_exp_f32_e32 v100, v100
	v_exp_f32_e32 v84, v84
	v_add_f32_e32 v128, v83, v128
	v_add_f32_e32 v121, v99, v121
	s_add_u32 vcc_lo, s0, s36
	s_addc_u32 vcc_hi, s1, s37
	s_add_i32 s19, s62, s95
	s_mov_b32 m0, s19
	ds_read_b64_tr_b16 v[122:123], v217 offset:5632
	ds_read_b64_tr_b16 v[124:125], v217 offset:7680
	global_load_lds_dwordx4 v160, vcc
	s_waitcnt lgkmcnt(4)
	v_mfma_f32_32x32x16_bf16 v[32:47], v[10:13], v[112:115], v[32:47]
	v_exp_f32_e32 v101, v101
	v_exp_f32_e32 v85, v85
	v_add_f32_e32 v126, v84, v128
	v_add_f32_e32 v121, v100, v121
	ds_read_b64_tr_b16 v[112:113], v217 offset:8192
	ds_read_b64_tr_b16 v[114:115], v217 offset:10240
	s_waitcnt lgkmcnt(4)
	v_mfma_f32_32x32x16_bf16 v[48:63], v[10:13], v[116:119], v[48:63]
	v_exp_f32_e32 v102, v102
	v_exp_f32_e32 v86, v86
	v_add_f32_e32 v126, v85, v126
	v_add_f32_e32 v121, v101, v121
	s_add_i32 m0, s19, 0x2000
	ds_read_b64_tr_b16 v[116:117], v217 offset:8704
	ds_read_b64_tr_b16 v[118:119], v217 offset:10752
	global_load_lds_dwordx4 v14, vcc
	s_waitcnt lgkmcnt(4)
	v_mfma_f32_32x32x16_bf16 v[64:79], v[10:13], v[122:125], v[64:79]
	v_exp_f32_e32 v103, v103
	v_exp_f32_e32 v87, v87
	v_add_f32_e32 v122, v86, v126
	v_add_f32_e32 v121, v102, v121
	ds_read_b64_tr_b16 v[10:11], v217 offset:9216
	ds_read_b64_tr_b16 v[12:13], v217 offset:11264
	s_waitcnt lgkmcnt(4)
	v_mfma_f32_32x32x16_bf16 v[16:31], v[6:9], v[112:115], v[16:31]
	v_exp_f32_e32 v104, v104
	v_exp_f32_e32 v88, v88
	v_add_f32_e32 v122, v87, v122
	v_add_f32_e32 v121, v103, v121
	ds_read_b64_tr_b16 v[112:113], v217 offset:9728
	ds_read_b64_tr_b16 v[114:115], v217 offset:11776
	s_waitcnt lgkmcnt(4)
	v_mfma_f32_32x32x16_bf16 v[32:47], v[6:9], v[116:119], v[32:47]
	v_exp_f32_e32 v105, v105
	v_exp_f32_e32 v89, v89
	v_add_f32_e32 v116, v88, v122
	v_add_f32_e32 v117, v104, v121
	ds_read_b64_tr_b16 v[122:123], v217 offset:12288
	ds_read_b64_tr_b16 v[124:125], v217 offset:14336
	s_waitcnt lgkmcnt(4)
	v_mfma_f32_32x32x16_bf16 v[48:63], v[6:9], v[10:13], v[48:63]
	v_exp_f32_e32 v106, v106
	v_exp_f32_e32 v90, v90
	v_add_f32_e32 v10, v89, v116
	v_add_f32_e32 v11, v105, v117
	ds_read_b64_tr_b16 v[126:127], v217 offset:12800
	ds_read_b64_tr_b16 v[128:129], v217 offset:14848
	s_waitcnt lgkmcnt(4)
	v_mfma_f32_32x32x16_bf16 v[64:79], v[6:9], v[112:115], v[64:79]
	v_exp_f32_e32 v107, v107
	v_exp_f32_e32 v91, v91
	v_add_f32_e32 v6, v90, v10
	v_add_f32_e32 v7, v106, v11
	v_add_u32_e32 v8, s18, v209
	ds_read_b64_tr_b16 v[130:131], v217 offset:13312
	ds_read_b64_tr_b16 v[132:133], v217 offset:15360
	ds_read_b128 v[116:119], v8
	ds_read_b128 v[112:115], v8 offset:4096
	s_waitcnt lgkmcnt(6)
	v_mfma_f32_32x32x16_bf16 v[16:31], v[2:5], v[122:125], v[16:31]
	v_exp_f32_e32 v108, v108
	v_exp_f32_e32 v92, v92
	v_add_f32_e32 v121, v91, v6
	v_add_f32_e32 v134, v107, v7
	v_add_u32_e32 v6, s18, v210
	ds_read_b64_tr_b16 v[122:123], v217 offset:13824
	ds_read_b64_tr_b16 v[124:125], v217 offset:15872
	ds_read_b128 v[10:13], v6
	ds_read_b128 v[6:9], v6 offset:4096
	s_waitcnt lgkmcnt(8)
	v_mfma_f32_32x32x16_bf16 v[32:47], v[2:5], v[126:129], v[32:47]
	v_exp_f32_e32 v109, v109
	v_exp_f32_e32 v93, v93
	v_add_f32_e32 v121, v92, v121
	v_add_f32_e32 v126, v108, v134
	s_waitcnt lgkmcnt(6)
	v_mfma_f32_32x32x16_bf16 v[48:63], v[2:5], v[130:133], v[48:63]
	v_exp_f32_e32 v110, v110
	v_exp_f32_e32 v94, v94
	v_add_f32_e32 v121, v93, v121
	v_add_f32_e32 v126, v109, v126
	s_waitcnt lgkmcnt(2)
	v_mfma_f32_32x32x16_bf16 v[64:79], v[2:5], v[122:125], v[64:79]
	v_exp_f32_e32 v111, v111
	v_exp_f32_e32 v95, v95
	v_add_f32_e32 v2, v94, v121
	v_add_f32_e32 v3, v110, v126
	s_nop 0
	v_add_f32_e32 v3, v111, v3
	v_add_f32_e32 v2, v95, v2
	v_add_f32_e32 v2, v3, v2
	v_mov_b32_e32 v3, v2
	s_nop 1
	v_permlane32_swap_b32_e32 v2, v3
	v_cmp_neq_f32_e32 vcc, 1.0, v120
	s_cbranch_vccnz .Lmy_resc_a2_2

.Lmy_resc_a2_1:
	s_and_saveexec_b64 s[4:5], s[46:47]
	ds_write_b32 v188, v0 offset:128
	s_or_b64 exec, exec, s[4:5]
	s_waitcnt lgkmcnt(0)
	v_add_u32_e32 v96, s2, v170
	ds_read_b128 v[2:5], v96 offset:224
	ds_read_b128 v[88:91], v96 offset:192
	ds_read_b128 v[92:95], v96 offset:160
	ds_read_b128 v[96:99], v96 offset:128
	s_waitcnt lgkmcnt(0)
	v_pk_mul_f32 v[28:29], v[28:29], v[2:3]
	v_pk_mul_f32 v[24:25], v[24:25], v[88:89]
	v_pk_mul_f32 v[20:21], v[20:21], v[92:93]
	v_pk_mul_f32 v[30:31], v[30:31], v[4:5]
	v_pk_mul_f32 v[26:27], v[26:27], v[90:91]
	v_pk_mul_f32 v[22:23], v[22:23], v[94:95]
	v_pk_mul_f32 v[18:19], v[18:19], v[98:99]
	v_pk_mul_f32 v[16:17], v[16:17], v[96:97]
	v_pk_mul_f32 v[44:45], v[44:45], v[2:3]
	v_pk_mul_f32 v[40:41], v[40:41], v[88:89]
	v_pk_mul_f32 v[36:37], v[36:37], v[92:93]
	v_pk_mul_f32 v[46:47], v[46:47], v[4:5]
	v_pk_mul_f32 v[42:43], v[42:43], v[90:91]
	v_pk_mul_f32 v[38:39], v[38:39], v[94:95]
	v_pk_mul_f32 v[34:35], v[34:35], v[98:99]
	v_pk_mul_f32 v[32:33], v[32:33], v[96:97]
	v_pk_mul_f32 v[60:61], v[60:61], v[2:3]
	v_pk_mul_f32 v[56:57], v[56:57], v[88:89]
	v_pk_mul_f32 v[52:53], v[52:53], v[92:93]
	v_pk_mul_f32 v[62:63], v[62:63], v[4:5]
	v_pk_mul_f32 v[58:59], v[58:59], v[90:91]
	v_pk_mul_f32 v[54:55], v[54:55], v[94:95]
	v_pk_mul_f32 v[50:51], v[50:51], v[98:99]
	v_pk_mul_f32 v[48:49], v[48:49], v[96:97]
	v_pk_mul_f32 v[76:77], v[76:77], v[2:3]
	v_pk_mul_f32 v[72:73], v[72:73], v[88:89]
	v_pk_mul_f32 v[68:69], v[68:69], v[92:93]
	v_pk_mul_f32 v[78:79], v[78:79], v[4:5]
	v_pk_mul_f32 v[74:75], v[74:75], v[90:91]
	v_pk_mul_f32 v[70:71], v[70:71], v[94:95]
	v_pk_mul_f32 v[66:67], v[66:67], v[98:99]
	v_pk_mul_f32 v[64:65], v[64:65], v[96:97]
	s_branch .LBB0_323
.Lmy_resc_a2_2:
	s_and_saveexec_b64 s[18:19], s[46:47]
	ds_write_b32 v188, v120 offset:128
	s_or_b64 exec, exec, s[18:19]
	s_waitcnt lgkmcnt(0)
	v_add_u32_e32 v4, s2, v170
	ds_read_b128 v[122:125], v4 offset:224
	ds_read_b128 v[126:129], v4 offset:192
	ds_read_b128 v[130:133], v4 offset:160
	ds_read_b128 v[134:137], v4 offset:128
	s_waitcnt lgkmcnt(0)
	v_pk_mul_f32 v[28:29], v[28:29], v[122:123]
	v_pk_mul_f32 v[24:25], v[24:25], v[126:127]
	v_pk_mul_f32 v[20:21], v[20:21], v[130:131]
	v_pk_mul_f32 v[30:31], v[30:31], v[124:125]
	v_pk_mul_f32 v[26:27], v[26:27], v[128:129]
	v_pk_mul_f32 v[22:23], v[22:23], v[132:133]
	v_pk_mul_f32 v[18:19], v[18:19], v[136:137]
	v_pk_mul_f32 v[16:17], v[16:17], v[134:135]
	v_pk_mul_f32 v[44:45], v[44:45], v[122:123]
	v_pk_mul_f32 v[40:41], v[40:41], v[126:127]
	v_pk_mul_f32 v[36:37], v[36:37], v[130:131]
	v_pk_mul_f32 v[46:47], v[46:47], v[124:125]
	v_pk_mul_f32 v[42:43], v[42:43], v[128:129]
	v_pk_mul_f32 v[38:39], v[38:39], v[132:133]
	v_pk_mul_f32 v[34:35], v[34:35], v[136:137]
	v_pk_mul_f32 v[32:33], v[32:33], v[134:135]
	v_pk_mul_f32 v[60:61], v[60:61], v[122:123]
	v_pk_mul_f32 v[56:57], v[56:57], v[126:127]
	v_pk_mul_f32 v[52:53], v[52:53], v[130:131]
	v_pk_mul_f32 v[62:63], v[62:63], v[124:125]
	v_pk_mul_f32 v[58:59], v[58:59], v[128:129]
	v_pk_mul_f32 v[54:55], v[54:55], v[132:133]
	v_pk_mul_f32 v[50:51], v[50:51], v[136:137]
	v_pk_mul_f32 v[48:49], v[48:49], v[134:135]
	v_pk_mul_f32 v[76:77], v[76:77], v[122:123]
	v_pk_mul_f32 v[72:73], v[72:73], v[126:127]
	v_pk_mul_f32 v[68:69], v[68:69], v[130:131]
	v_pk_mul_f32 v[78:79], v[78:79], v[124:125]
	v_pk_mul_f32 v[74:75], v[74:75], v[128:129]
	v_pk_mul_f32 v[70:71], v[70:71], v[132:133]
	v_pk_mul_f32 v[66:67], v[66:67], v[136:137]
	v_pk_mul_f32 v[64:65], v[64:65], v[134:135]
	s_branch .LBB0_337
